# stacked: step-head prefetch + dilated-attention bias-LUT reads one ahead + trimmed FoX band-step causal masks
# speedup vs baseline: 1.0189x; 1.0097x over previous
.LBB0_100:
	v_add_co_u32_e32 v8, vcc, 0x8000, v4
	s_mov_b32 s1, 0x10000
	s_nop 0
	v_addc_co_u32_e32 v9, vcc, 0, v5, vcc
	global_load_dwordx4 v[146:149], v[8:9], off
	v_add_co_u32_e32 v8, vcc, 0xa000, v4
	s_nop 1
	v_addc_co_u32_e32 v9, vcc, 0, v5, vcc
	global_load_dwordx4 v[150:153], v[8:9], off
	v_add_co_u32_e32 v8, vcc, 0xc000, v4
	s_nop 1
	v_addc_co_u32_e32 v9, vcc, 0, v5, vcc
	global_load_dwordx4 v[154:157], v[8:9], off
	v_add_co_u32_e32 v8, vcc, 0xe000, v4
	s_nop 1
	v_addc_co_u32_e32 v9, vcc, 0, v5, vcc
	global_load_dwordx4 v[158:161], v[8:9], off
	v_add_co_u32_e32 v8, vcc, s1, v4
	s_add_i32 s1, 0, 0x18000
	s_nop 0
	v_addc_co_u32_e32 v9, vcc, 0, v5, vcc
	global_load_dwordx4 v[162:165], v[8:9], off
	v_add_co_u32_e32 v8, vcc, 0x12000, v4
	s_cmp_eq_u32 s81, 0
	s_nop 0
	v_addc_co_u32_e32 v9, vcc, 0, v5, vcc
	global_load_dwordx4 v[166:169], v[8:9], off
	v_add_co_u32_e32 v8, vcc, 0x14000, v4
	s_cselect_b64 s[6:7], -1, 0
	s_nop 0
	v_addc_co_u32_e32 v9, vcc, 0, v5, vcc
	v_add_co_u32_e32 v4, vcc, 0x16000, v4
	global_load_dwordx4 v[170:173], v[8:9], off
	s_nop 0
	v_addc_co_u32_e32 v5, vcc, 0, v5, vcc
	global_load_dwordx4 v[174:177], v[4:5], off
	v_lshlrev_b32_e32 v4, 2, v6
	v_and_b32_e32 v4, 12, v4
	v_bfe_u32 v5, v6, 2, 2
	v_or_b32_e32 v8, v4, v5
	v_bitop3_b32 v4, v4, v226, v5 bitop3:0x36
	v_lshl_add_u32 v9, v227, 8, s80
	v_lshl_add_u32 v10, v4, 4, v9
	v_bitop3_b32 v232, v226, v8, 2 bitop3:0x36
	v_lshl_add_u32 v232, v232, 4, v9
	v_bitop3_b32 v236, v226, v8, 4 bitop3:0x36
	v_lshl_add_u32 v236, v236, 4, v9
	v_bitop3_b32 v237, v226, v8, 6 bitop3:0x36
	v_lshl_add_u32 v237, v237, 4, v9
	v_bitop3_b32 v238, v226, v8, 8 bitop3:0x36
	v_lshl_add_u32 v238, v238, 4, v9
	v_bitop3_b32 v239, v226, v8, 10 bitop3:0x36
	v_lshl_add_u32 v239, v239, 4, v9
	v_bitop3_b32 v240, v226, v8, 12 bitop3:0x36
	v_lshl_add_u32 v240, v240, 4, v9
	v_bitop3_b32 v100, v226, v8, 14 bitop3:0x36
	v_lshl_add_u32 v100, v100, 4, v9
	ds_read_b128 v[4:7], v10
	ds_read_b128 v[244:247], v232
	s_waitcnt vmcnt(15) lgkmcnt(1)
	v_mfma_f32_32x32x16_bf16 v[64:79], v[4:7], v[0:3], 0
	s_and_b64 s[28:29], s[12:13], s[6:7]
	s_and_b64 vcc, exec, s[28:29]
	ds_read_b128 v[4:7], v236
	s_waitcnt vmcnt(14) lgkmcnt(1)
	v_mfma_f32_32x32x16_bf16 v[64:79], v[244:247], v[202:205], v[64:79]
	ds_read_b128 v[244:247], v237
	s_waitcnt vmcnt(13) lgkmcnt(1)
	v_mfma_f32_32x32x16_bf16 v[64:79], v[4:7], v[198:201], v[64:79]
	ds_read_b128 v[4:7], v238
	s_waitcnt vmcnt(12) lgkmcnt(1)
	v_mfma_f32_32x32x16_bf16 v[64:79], v[244:247], v[194:197], v[64:79]
	ds_read_b128 v[244:247], v239
	s_waitcnt vmcnt(11) lgkmcnt(1)
	v_mfma_f32_32x32x16_bf16 v[64:79], v[4:7], v[190:193], v[64:79]
	ds_read_b128 v[4:7], v240
	s_waitcnt vmcnt(10) lgkmcnt(1)
	v_mfma_f32_32x32x16_bf16 v[64:79], v[244:247], v[186:189], v[64:79]
	ds_read_b128 v[244:247], v100
	s_waitcnt vmcnt(9) lgkmcnt(1)
	v_mfma_f32_32x32x16_bf16 v[64:79], v[4:7], v[182:185], v[64:79]
	ds_read_b128 v[4:7], v10 offset:8192
	s_waitcnt vmcnt(8) lgkmcnt(1)
	v_mfma_f32_32x32x16_bf16 v[64:79], v[244:247], v[178:181], v[64:79]
	ds_read_b128 v[244:247], v232 offset:8192
	s_waitcnt lgkmcnt(1)
	v_mfma_f32_32x32x16_bf16 v[48:63], v[4:7], v[0:3], 0
	ds_read_b128 v[4:7], v236 offset:8192
	s_waitcnt lgkmcnt(1)
	v_mfma_f32_32x32x16_bf16 v[48:63], v[244:247], v[202:205], v[48:63]
	ds_read_b128 v[244:247], v237 offset:8192
	s_waitcnt lgkmcnt(1)
	v_mfma_f32_32x32x16_bf16 v[48:63], v[4:7], v[198:201], v[48:63]
	ds_read_b128 v[4:7], v238 offset:8192
	s_waitcnt lgkmcnt(1)
	v_mfma_f32_32x32x16_bf16 v[48:63], v[244:247], v[194:197], v[48:63]
	ds_read_b128 v[244:247], v239 offset:8192
	s_waitcnt lgkmcnt(1)
	v_mfma_f32_32x32x16_bf16 v[48:63], v[4:7], v[190:193], v[48:63]
	ds_read_b128 v[4:7], v240 offset:8192
	s_waitcnt lgkmcnt(1)
	v_mfma_f32_32x32x16_bf16 v[48:63], v[244:247], v[186:189], v[48:63]
	ds_read_b128 v[244:247], v100 offset:8192
	s_waitcnt lgkmcnt(1)
	v_mfma_f32_32x32x16_bf16 v[48:63], v[4:7], v[182:185], v[48:63]
	ds_read_b128 v[4:7], v10 offset:16384
	s_waitcnt lgkmcnt(1)
	v_mfma_f32_32x32x16_bf16 v[48:63], v[244:247], v[178:181], v[48:63]
	ds_read_b128 v[244:247], v232 offset:16384
	s_waitcnt lgkmcnt(1)
	v_mfma_f32_32x32x16_bf16 v[32:47], v[4:7], v[0:3], 0
	ds_read_b128 v[4:7], v236 offset:16384
	s_waitcnt lgkmcnt(1)
	v_mfma_f32_32x32x16_bf16 v[32:47], v[244:247], v[202:205], v[32:47]
	ds_read_b128 v[244:247], v237 offset:16384
	s_waitcnt lgkmcnt(1)
	v_mfma_f32_32x32x16_bf16 v[32:47], v[4:7], v[198:201], v[32:47]
	ds_read_b128 v[4:7], v238 offset:16384
	s_waitcnt lgkmcnt(1)
	v_mfma_f32_32x32x16_bf16 v[32:47], v[244:247], v[194:197], v[32:47]
	ds_read_b128 v[244:247], v239 offset:16384
	s_waitcnt lgkmcnt(1)
	v_mfma_f32_32x32x16_bf16 v[32:47], v[4:7], v[190:193], v[32:47]
	ds_read_b128 v[4:7], v240 offset:16384
	s_waitcnt lgkmcnt(1)
	v_mfma_f32_32x32x16_bf16 v[32:47], v[244:247], v[186:189], v[32:47]
	ds_read_b128 v[244:247], v100 offset:16384
	s_waitcnt lgkmcnt(1)
	v_mfma_f32_32x32x16_bf16 v[32:47], v[4:7], v[182:185], v[32:47]
	ds_read_b128 v[4:7], v10 offset:24576
	s_waitcnt lgkmcnt(1)
	v_mfma_f32_32x32x16_bf16 v[32:47], v[244:247], v[178:181], v[32:47]
	ds_read_b128 v[244:247], v232 offset:24576
	s_waitcnt lgkmcnt(1)
	v_mfma_f32_32x32x16_bf16 v[16:31], v[4:7], v[0:3], 0
	ds_read_b128 v[4:7], v236 offset:24576
	s_waitcnt lgkmcnt(1)
	v_mfma_f32_32x32x16_bf16 v[16:31], v[244:247], v[202:205], v[16:31]
	ds_read_b128 v[244:247], v237 offset:24576
	s_waitcnt lgkmcnt(1)
	v_mfma_f32_32x32x16_bf16 v[16:31], v[4:7], v[198:201], v[16:31]
	ds_read_b128 v[4:7], v238 offset:24576
	s_waitcnt lgkmcnt(1)
	v_mfma_f32_32x32x16_bf16 v[16:31], v[244:247], v[194:197], v[16:31]
	ds_read_b128 v[244:247], v239 offset:24576
	s_waitcnt lgkmcnt(1)
	v_mfma_f32_32x32x16_bf16 v[16:31], v[4:7], v[190:193], v[16:31]
	ds_read_b128 v[4:7], v240 offset:24576
	s_waitcnt lgkmcnt(1)
	v_mfma_f32_32x32x16_bf16 v[16:31], v[244:247], v[186:189], v[16:31]
	ds_read_b128 v[244:247], v100 offset:24576
	s_waitcnt lgkmcnt(1)
	v_mfma_f32_32x32x16_bf16 v[16:31], v[4:7], v[182:185], v[16:31]
	ds_read_b128 v[4:7], v10 offset:32768
	s_waitcnt lgkmcnt(1)
	v_mfma_f32_32x32x16_bf16 v[16:31], v[244:247], v[178:181], v[16:31]
	ds_read_b128 v[244:247], v232 offset:32768
	s_waitcnt lgkmcnt(1)
	v_mfma_f32_32x32x16_bf16 v[0:15], v[4:7], v[0:3], 0
	ds_read_b128 v[232:235], v236 offset:32768
	s_waitcnt lgkmcnt(1)
	v_mfma_f32_32x32x16_bf16 v[0:15], v[244:247], v[202:205], v[0:15]
	ds_read_b128 v[244:247], v237 offset:32768
	s_waitcnt lgkmcnt(1)
	v_mfma_f32_32x32x16_bf16 v[0:15], v[232:235], v[198:201], v[0:15]
	v_mov_b32_e32 v202, 0xff800000
	ds_read_b128 v[232:235], v238 offset:32768
	s_waitcnt lgkmcnt(1)
	v_mfma_f32_32x32x16_bf16 v[0:15], v[244:247], v[194:197], v[0:15]
	ds_read_b128 v[244:247], v239 offset:32768
	s_waitcnt lgkmcnt(1)
	v_mfma_f32_32x32x16_bf16 v[0:15], v[232:235], v[190:193], v[0:15]
	v_mov_b32_e32 v195, 0xff800000
	v_mov_b32_e32 v194, 0xff800000
	v_mov_b32_e32 v197, 0xff800000
	v_mov_b32_e32 v196, 0xff800000
	ds_read_b128 v[232:235], v240 offset:32768
	s_waitcnt lgkmcnt(1)
	v_mfma_f32_32x32x16_bf16 v[0:15], v[244:247], v[186:189], v[0:15]
	v_mov_b32_e32 v190, 0xff800000
	v_mov_b32_e32 v191, 0xff800000
	v_mov_b32_e32 v193, 0xff800000
	v_mov_b32_e32 v192, 0xff800000
	ds_read_b128 v[244:247], v100 offset:32768
	s_waitcnt lgkmcnt(1)
	v_mfma_f32_32x32x16_bf16 v[0:15], v[232:235], v[182:185], v[0:15]
	v_mov_b32_e32 v100, 0xff800000
	v_mov_b32_e32 v186, 0xff800000
	v_mov_b32_e32 v189, 0xff800000
	v_mov_b32_e32 v188, 0xff800000
	s_waitcnt lgkmcnt(0)
	v_mfma_f32_32x32x16_bf16 v[0:15], v[244:247], v[178:181], v[0:15]
	v_lshlrev_b32_e32 v180, 2, v226
	v_sub_u32_e32 v181, v227, v180
	v_lshl_add_u32 v187, v181, 2, s1
	v_mov_b32_e32 v178, 0xff800000
	v_mov_b32_e32 v182, 0xff800000
	v_mov_b32_e32 v184, 0xff800000
	v_mov_b32_e32 v183, 0xff800000
	v_mov_b32_e32 v185, 0xff800000
	s_cbranch_vccnz .LBB0_102
	ds_read2_b32 v[244:245], v187 offset0:159 offset1:160
	v_cmp_gt_i32_e32 vcc, 2, v181
	s_mov_b32 s1, 0xff800000
	ds_read2_b32 v[246:247], v187 offset0:157 offset1:158
	s_waitcnt lgkmcnt(1)
	v_pk_add_f32 v[64:65], v[64:65], v[244:245] op_sel:[0,1] op_sel_hi:[1,0]
	s_nop 0
	v_cndmask_b32_e32 v100, v220, v65, vcc
	v_cmp_gt_i32_e32 vcc, 1, v181
	s_nop 1
	v_cndmask_b32_e32 v182, v220, v64, vcc
	v_cmp_gt_i32_e32 vcc, 4, v181
	v_max3_f32 v179, v182, s1, v100
	ds_read2_b32 v[244:245], v187 offset0:151 offset1:152
	s_waitcnt lgkmcnt(1)
	v_pk_add_f32 v[64:65], v[66:67], v[246:247] op_sel:[0,1] op_sel_hi:[1,0]
	s_nop 0
	v_cndmask_b32_e32 v183, v220, v65, vcc
	v_cmp_gt_i32_e32 vcc, 3, v181
	s_nop 1
	v_cndmask_b32_e32 v184, v220, v64, vcc
	v_cmp_gt_i32_e32 vcc, 10, v181
	v_max3_f32 v66, v179, v184, v183
	ds_read2_b32 v[246:247], v187 offset0:149 offset1:150
	s_waitcnt lgkmcnt(1)
	v_pk_add_f32 v[64:65], v[68:69], v[244:245] op_sel:[0,1] op_sel_hi:[1,0]
	s_nop 0
	v_cndmask_b32_e32 v185, v220, v65, vcc
	v_cmp_gt_i32_e32 vcc, 9, v181
	s_nop 1
	v_cndmask_b32_e32 v186, v220, v64, vcc
	v_cmp_gt_i32_e32 vcc, 12, v181
	v_max3_f32 v66, v66, v186, v185
	ds_read2_b32 v[244:245], v187 offset0:143 offset1:144
	s_waitcnt lgkmcnt(1)
	v_pk_add_f32 v[64:65], v[70:71], v[246:247] op_sel:[0,1] op_sel_hi:[1,0]
	s_nop 0
	v_cndmask_b32_e32 v188, v220, v65, vcc
	v_cmp_gt_i32_e32 vcc, 11, v181
	s_nop 1
	v_cndmask_b32_e32 v189, v220, v64, vcc
	v_cmp_gt_i32_e32 vcc, 18, v181
	v_max3_f32 v66, v66, v189, v188
	ds_read2_b32 v[246:247], v187 offset0:141 offset1:142
	s_waitcnt lgkmcnt(1)
	v_pk_add_f32 v[64:65], v[72:73], v[244:245] op_sel:[0,1] op_sel_hi:[1,0]
	s_nop 0
	v_cndmask_b32_e32 v191, v220, v65, vcc
	v_cmp_gt_i32_e32 vcc, 17, v181
	s_nop 1
	v_cndmask_b32_e32 v190, v220, v64, vcc
	v_cmp_gt_i32_e32 vcc, 20, v181
	v_max3_f32 v66, v66, v190, v191
	ds_read2_b32 v[244:245], v187 offset0:135 offset1:136
	s_waitcnt lgkmcnt(1)
	v_pk_add_f32 v[64:65], v[74:75], v[246:247] op_sel:[0,1] op_sel_hi:[1,0]
	s_nop 0
	v_cndmask_b32_e32 v192, v220, v65, vcc
	v_cmp_gt_i32_e32 vcc, 19, v181
	s_nop 1
	v_cndmask_b32_e32 v193, v220, v64, vcc
	v_cmp_gt_i32_e32 vcc, 26, v181
	v_max3_f32 v66, v66, v193, v192
	ds_read2_b32 v[246:247], v187 offset0:133 offset1:134
	s_waitcnt lgkmcnt(1)
	v_pk_add_f32 v[64:65], v[76:77], v[244:245] op_sel:[0,1] op_sel_hi:[1,0]
	s_nop 0
	v_cndmask_b32_e32 v194, v220, v65, vcc
	v_cmp_gt_i32_e32 vcc, 25, v181
	s_nop 1
	v_cndmask_b32_e32 v195, v220, v64, vcc
	v_cmp_gt_i32_e32 vcc, 28, v181
	v_max3_f32 v66, v66, v195, v194
	s_waitcnt lgkmcnt(0)
	v_pk_add_f32 v[64:65], v[78:79], v[246:247] op_sel:[0,1] op_sel_hi:[1,0]
	s_nop 0
	v_cndmask_b32_e32 v196, v220, v65, vcc
	v_cmp_gt_i32_e32 vcc, 27, v181
	s_nop 1
	v_cndmask_b32_e32 v197, v220, v64, vcc
	v_max3_f32 v202, v66, v197, v196
